# K-loop: delayed priority drop also in the loop-back segment (s_setprio 0 after the first read batch at loop top, plus exit-path s_setprio 0)
# baseline (speedup 1.0000x reference)
; #define PG8_STAGE(bufoff, gbase, voff) do { _Pragma("unroll") for (int _i = 0; _i < 2; ++_i) \
;         __builtin_amdgcn_global_load_lds((const unsigned*)((const char*)(gbase) + (voff)[_i]), (PG8_LAS unsigned*)(lds + (bufoff) + ldsw + _i * 8192), 16, 0, 0); } while (0)
; #define PG8_LDA(dst, b, h) do { _Pragma("unroll") for (int m = 0; m < 4; ++m) _Pragma("unroll") for (int k = 0; k < 2; ++k) dst[m][k] = *(const PG8_LAS bf16x8*)(lds + PG8_SA(b, h) + aoff + m * 2048 + k * 1024); } while (0)
; #define PG8_LDB(dst, b, h) do { _Pragma("unroll") for (int n = 0; n < 2; ++n) _Pragma("unroll") for (int k = 0; k < 2; ++k) dst[n][k] = *(const PG8_LAS bf16x8*)(lds + PG8_SB(b, h) + boff + n * 2048 + k * 1024); } while (0)
; #define PG8_MMA(ai, bj, At, Bt) do { __builtin_amdgcn_s_setprio(1); _Pragma("unroll") for (int m = 0; m < 4; ++m) _Pragma("unroll") for (int n = 0; n < 2; ++n) _Pragma("unroll") for (int k = 0; k < 2; ++k) \
;         acc[ai][bj][m][n] = __builtin_amdgcn_mfma_f32_16x16x32_bf16(Bt[n][k], At[m][k], acc[ai][bj][m][n], 0, 0, 0); __builtin_amdgcn_s_setprio(0); } while (0)
; #define PG8_WAIT_V(n) asm volatile("s_waitcnt vmcnt(" #n ")" ::: "memory")
; #define PG8_WAIT_L(n) asm volatile("s_waitcnt lgkmcnt(" #n ")" ::: "memory")
; #define PG8_BAR __builtin_amdgcn_s_barrier()
; #define PG8_SCHED __builtin_amdgcn_sched_barrier(0)
; template <class Epi, class Sched, bool ALIGN_EPI = false, bool SP2 = false>
; __device__ __forceinline__ void gemm_phase(PG8_LAS unsigned char* lds, const Gemm g, const Sched& S, const Epi& E) {
;     ...
;         for (int t = 0; t < nt; t += 2) {
;             const bool last = (t == nt - 2);
;             const char* a1 = cA + (size_t)(t + 1) * kstep;
;             const char* a2 = last ? nA : cA + (size_t)(t + 2) * kstep; const char* b2 = last ? nB : cB + (size_t)(t + 2) * kstep;
;             const char* a3 = a2 + kstep; const char* b3 = b2 + kstep;
;             if (last && has_next) S.a_ready(nxt);
;             if constexpr (SP2) {
;             PG8_LDB(B0, 0, 0); PG8_LDB(B1, 0, 1); PG8_SCHED; PG8_LDA(At, 0, 0); PG8_STAGE(PG8_SA(1, 1), a1 + hstep, voffA);
;             PG8_WAIT_V(8); PG8_WAIT_L(0); PG8_BAR; PG8_MMA(0, 0, At, B0); PG8_MMA(0, 1, At, B1); PG8_BAR; PG8_SCHED;
;             PG8_LDA(At, 0, 1); PG8_STAGE(PG8_SB(0, 0), b2, voffB); PG8_STAGE(PG8_SB(0, 1), b2 + hstep, voffB); PG8_STAGE(PG8_SA(0, 0), a2, voffA);
.LBB0_441:
	ds_read_b128 v[130:133], v242
	ds_read_b128 v[134:137], v242 offset:1024
	ds_read_b128 v[138:141], v242 offset:2048
	ds_read_b128 v[142:145], v242 offset:3072
	ds_read_b128 v[146:149], v243
	ds_read_b128 v[150:153], v243 offset:1024
	ds_read_b128 v[154:157], v243 offset:2048
	ds_read_b128 v[158:161], v243 offset:3072
	s_setprio 0
	s_add_i32 s66, 0, 0x10000
	s_add_i32 s67, 0, 0x14000
	v_lshl_add_u64 v[206:207], s[42:43], 0, v[190:191]
	s_add_i32 m0, s93, 0xc000
	ds_read_b128 v[162:165], v230
	ds_read_b128 v[166:169], v230 offset:1024
	ds_read_b128 v[170:173], v230 offset:2048
	ds_read_b128 v[174:177], v230 offset:3072
	ds_read_b128 v[178:181], v230 offset:4096
	ds_read_b128 v[194:197], v230 offset:5120
	ds_read_b128 v[198:201], v230 offset:6144
	ds_read_b128 v[202:205], v230 offset:7168
	s_add_i32 s61, s44, 2
	s_add_u32 s64, s42, 0x80
	s_addc_u32 s45, s43, 0
	s_cmp_eq_u32 s99, s44
	s_cselect_b32 s45, s29, s45
	s_cselect_b32 s44, s28, s64
	s_cselect_b32 s65, s21, s60
	s_cselect_b32 s64, s20, s17
	global_load_lds_dwordx4 v[206:207], off
	s_add_i32 m0, s93, 0xe000
	v_lshl_add_u64 v[206:207], s[42:43], 0, v[192:193]
	global_load_lds_dwordx4 v[206:207], off
	s_setprio 1
	s_waitcnt vmcnt(8) lgkmcnt(0)
	s_barrier
	v_mfma_f32_16x16x32_bf16 v[126:129], v[130:133], v[162:165], v[126:129]
	v_mfma_f32_16x16x32_bf16 v[122:125], v[138:141], v[162:165], v[122:125]
	v_mfma_f32_16x16x32_bf16 v[110:113], v[130:133], v[170:173], v[110:113]
	v_mfma_f32_16x16x32_bf16 v[102:105], v[138:141], v[170:173], v[102:105]
	v_mfma_f32_16x16x32_bf16 v[94:97], v[130:133], v[178:181], v[94:97]
	v_mfma_f32_16x16x32_bf16 v[86:89], v[138:141], v[178:181], v[86:89]
	v_mfma_f32_16x16x32_bf16 v[78:81], v[130:133], v[198:201], v[78:81]
	v_mfma_f32_16x16x32_bf16 v[70:73], v[138:141], v[198:201], v[70:73]
	v_mfma_f32_16x16x32_bf16 v[126:129], v[134:137], v[166:169], v[126:129]
	v_mfma_f32_16x16x32_bf16 v[122:125], v[142:145], v[166:169], v[122:125]
	v_mfma_f32_16x16x32_bf16 v[110:113], v[134:137], v[174:177], v[110:113]
	v_mfma_f32_16x16x32_bf16 v[102:105], v[142:145], v[174:177], v[102:105]
	v_mfma_f32_16x16x32_bf16 v[94:97], v[134:137], v[194:197], v[94:97]
	v_mfma_f32_16x16x32_bf16 v[86:89], v[142:145], v[194:197], v[86:89]
	v_mfma_f32_16x16x32_bf16 v[78:81], v[134:137], v[202:205], v[78:81]
	v_mfma_f32_16x16x32_bf16 v[70:73], v[142:145], v[202:205], v[70:73]
	v_mfma_f32_16x16x32_bf16 v[118:121], v[146:149], v[162:165], v[118:121]
	v_mfma_f32_16x16x32_bf16 v[114:117], v[154:157], v[162:165], v[114:117]
	v_mfma_f32_16x16x32_bf16 v[106:109], v[146:149], v[170:173], v[106:109]
	v_mfma_f32_16x16x32_bf16 v[98:101], v[154:157], v[170:173], v[98:101]
	v_mfma_f32_16x16x32_bf16 v[90:93], v[146:149], v[178:181], v[90:93]
	v_mfma_f32_16x16x32_bf16 v[82:85], v[154:157], v[178:181], v[82:85]
	v_mfma_f32_16x16x32_bf16 v[74:77], v[146:149], v[198:201], v[74:77]
	v_mfma_f32_16x16x32_bf16 v[66:69], v[154:157], v[198:201], v[66:69]
	v_mfma_f32_16x16x32_bf16 v[118:121], v[150:153], v[166:169], v[118:121]
	v_mfma_f32_16x16x32_bf16 v[114:117], v[158:161], v[166:169], v[114:117]
	v_mfma_f32_16x16x32_bf16 v[106:109], v[150:153], v[174:177], v[106:109]
	v_mfma_f32_16x16x32_bf16 v[98:101], v[158:161], v[174:177], v[98:101]
	v_mfma_f32_16x16x32_bf16 v[90:93], v[150:153], v[194:197], v[90:93]
	v_mfma_f32_16x16x32_bf16 v[82:85], v[158:161], v[194:197], v[82:85]
	v_mfma_f32_16x16x32_bf16 v[74:77], v[150:153], v[202:205], v[74:77]
	v_mfma_f32_16x16x32_bf16 v[66:69], v[158:161], v[202:205], v[66:69]
	s_barrier
	ds_read_b128 v[162:165], v230 offset:16384
	ds_read_b128 v[166:169], v230 offset:17408
	ds_read_b128 v[170:173], v230 offset:18432
	ds_read_b128 v[174:177], v230 offset:19456
	ds_read_b128 v[178:181], v230 offset:20480
	ds_read_b128 v[194:197], v230 offset:21504
	ds_read_b128 v[198:201], v230 offset:22528
	ds_read_b128 v[202:205], v230 offset:23552
	s_setprio 0
	s_add_i32 s66, s66, s92
	s_mov_b32 m0, s66
	v_lshl_add_u64 v[206:207], s[64:65], 0, v[184:185]
	global_load_lds_dwordx4 v[206:207], off
	s_add_i32 m0, s66, 0x2000
	v_lshl_add_u64 v[208:209], s[64:65], 0, v[188:189]
	s_add_u32 s64, s64, s26
	s_addc_u32 s65, s65, 0
	s_add_i32 s66, s67, s92
	global_load_lds_dwordx4 v[208:209], off
	v_lshl_add_u64 v[210:211], s[64:65], 0, v[184:185]
	s_mov_b32 m0, s66
	v_lshl_add_u64 v[232:233], s[64:65], 0, v[188:189]
	global_load_lds_dwordx4 v[210:211], off
	s_add_i32 m0, s66, 0x2000
	v_lshl_add_u64 v[234:235], s[44:45], 0, v[182:183]
	global_load_lds_dwordx4 v[232:233], off
	s_mov_b32 m0, s93
	v_lshl_add_u64 v[236:237], s[44:45], 0, v[186:187]
	global_load_lds_dwordx4 v[234:235], off
	s_mov_b32 m0, s94
	s_nop 0
	global_load_lds_dwordx4 v[236:237], off
	s_setprio 1
	s_waitcnt vmcnt(8) lgkmcnt(0)
	s_barrier
; #define PG8_STAGE(bufoff, gbase, voff) do { _Pragma("unroll") for (int _i = 0; _i < 2; ++_i) \
;         __builtin_amdgcn_global_load_lds((const unsigned*)((const char*)(gbase) + (voff)[_i]), (PG8_LAS unsigned*)(lds + (bufoff) + ldsw + _i * 8192), 16, 0, 0); } while (0)
; #define PG8_LDA(dst, b, h) do { _Pragma("unroll") for (int m = 0; m < 4; ++m) _Pragma("unroll") for (int k = 0; k < 2; ++k) dst[m][k] = *(const PG8_LAS bf16x8*)(lds + PG8_SA(b, h) + aoff + m * 2048 + k * 1024); } while (0)
; #define PG8_LDB(dst, b, h) do { _Pragma("unroll") for (int n = 0; n < 2; ++n) _Pragma("unroll") for (int k = 0; k < 2; ++k) dst[n][k] = *(const PG8_LAS bf16x8*)(lds + PG8_SB(b, h) + boff + n * 2048 + k * 1024); } while (0)
; #define PG8_MMA(ai, bj, At, Bt) do { __builtin_amdgcn_s_setprio(1); _Pragma("unroll") for (int m = 0; m < 4; ++m) _Pragma("unroll") for (int n = 0; n < 2; ++n) _Pragma("unroll") for (int k = 0; k < 2; ++k) \
;         acc[ai][bj][m][n] = __builtin_amdgcn_mfma_f32_16x16x32_bf16(Bt[n][k], At[m][k], acc[ai][bj][m][n], 0, 0, 0); __builtin_amdgcn_s_setprio(0); } while (0)
; #define PG8_WAIT_V(n) asm volatile("s_waitcnt vmcnt(" #n ")" ::: "memory")
; #define PG8_WAIT_L(n) asm volatile("s_waitcnt lgkmcnt(" #n ")" ::: "memory")
; #define PG8_BAR __builtin_amdgcn_s_barrier()
; #define PG8_SCHED __builtin_amdgcn_sched_barrier(0)
; template <class Epi, class Sched, bool ALIGN_EPI = false, bool SP2 = false>
; __device__ __forceinline__ void gemm_phase(PG8_LAS unsigned char* lds, const Gemm g, const Sched& S, const Epi& E) {
;     ...
;             PG8_WAIT_V(8); PG8_WAIT_L(0); PG8_BAR; PG8_MMA(1, 0, At, B0); PG8_MMA(1, 1, At, B1); PG8_BAR; PG8_SCHED;
;             PG8_LDB(B0, 1, 0); PG8_LDB(B1, 1, 1); PG8_SCHED; PG8_LDA(At, 1, 0); PG8_STAGE(PG8_SA(0, 1), a2 + hstep, voffA);
;             PG8_WAIT_V(8); PG8_WAIT_L(0); PG8_BAR; PG8_MMA(0, 0, At, B0); PG8_MMA(0, 1, At, B1); PG8_BAR; PG8_SCHED;
	v_mfma_f32_16x16x32_bf16 v[62:65], v[130:133], v[162:165], v[62:65]
	v_mfma_f32_16x16x32_bf16 v[54:57], v[138:141], v[162:165], v[54:57]
	v_mfma_f32_16x16x32_bf16 v[46:49], v[130:133], v[170:173], v[46:49]
	v_mfma_f32_16x16x32_bf16 v[38:41], v[138:141], v[170:173], v[38:41]
	v_mfma_f32_16x16x32_bf16 v[30:33], v[130:133], v[178:181], v[30:33]
	v_mfma_f32_16x16x32_bf16 v[22:25], v[138:141], v[178:181], v[22:25]
	v_mfma_f32_16x16x32_bf16 v[14:17], v[130:133], v[198:201], v[14:17]
	v_mfma_f32_16x16x32_bf16 v[6:9], v[138:141], v[198:201], v[6:9]
	v_mfma_f32_16x16x32_bf16 v[62:65], v[134:137], v[166:169], v[62:65]
	v_mfma_f32_16x16x32_bf16 v[54:57], v[142:145], v[166:169], v[54:57]
	v_mfma_f32_16x16x32_bf16 v[46:49], v[134:137], v[174:177], v[46:49]
	v_mfma_f32_16x16x32_bf16 v[38:41], v[142:145], v[174:177], v[38:41]
	v_mfma_f32_16x16x32_bf16 v[30:33], v[134:137], v[194:197], v[30:33]
	v_mfma_f32_16x16x32_bf16 v[22:25], v[142:145], v[194:197], v[22:25]
	v_mfma_f32_16x16x32_bf16 v[14:17], v[134:137], v[202:205], v[14:17]
	v_mfma_f32_16x16x32_bf16 v[6:9], v[142:145], v[202:205], v[6:9]
	v_mfma_f32_16x16x32_bf16 v[58:61], v[146:149], v[162:165], v[58:61]
	v_mfma_f32_16x16x32_bf16 v[50:53], v[154:157], v[162:165], v[50:53]
	v_mfma_f32_16x16x32_bf16 v[42:45], v[146:149], v[170:173], v[42:45]
	v_mfma_f32_16x16x32_bf16 v[34:37], v[154:157], v[170:173], v[34:37]
	v_mfma_f32_16x16x32_bf16 v[26:29], v[146:149], v[178:181], v[26:29]
	v_mfma_f32_16x16x32_bf16 v[18:21], v[154:157], v[178:181], v[18:21]
	v_mfma_f32_16x16x32_bf16 v[10:13], v[146:149], v[198:201], v[10:13]
	v_mfma_f32_16x16x32_bf16 v[2:5], v[154:157], v[198:201], v[2:5]
	v_mfma_f32_16x16x32_bf16 v[58:61], v[150:153], v[166:169], v[58:61]
	v_mfma_f32_16x16x32_bf16 v[50:53], v[158:161], v[166:169], v[50:53]
	v_mfma_f32_16x16x32_bf16 v[42:45], v[150:153], v[174:177], v[42:45]
	v_mfma_f32_16x16x32_bf16 v[34:37], v[158:161], v[174:177], v[34:37]
	v_mfma_f32_16x16x32_bf16 v[26:29], v[150:153], v[194:197], v[26:29]
	v_mfma_f32_16x16x32_bf16 v[18:21], v[158:161], v[194:197], v[18:21]
	v_mfma_f32_16x16x32_bf16 v[10:13], v[150:153], v[202:205], v[10:13]
	v_mfma_f32_16x16x32_bf16 v[2:5], v[158:161], v[202:205], v[2:5]
	s_barrier
	ds_read_b128 v[162:165], v230 offset:32768
	ds_read_b128 v[166:169], v230 offset:33792
	ds_read_b128 v[170:173], v230 offset:34816
	ds_read_b128 v[174:177], v230 offset:35840
	ds_read_b128 v[178:181], v230 offset:36864
	ds_read_b128 v[194:197], v230 offset:37888
	ds_read_b128 v[198:201], v230 offset:38912
	ds_read_b128 v[202:205], v230 offset:39936
	ds_read_b128 v[130:133], v244
	ds_read_b128 v[134:137], v244 offset:1024
	ds_read_b128 v[138:141], v244 offset:2048
	ds_read_b128 v[142:145], v244 offset:3072
	ds_read_b128 v[146:149], v245
	ds_read_b128 v[150:153], v245 offset:1024
	ds_read_b128 v[154:157], v245 offset:2048
	ds_read_b128 v[158:161], v245 offset:3072
	s_setprio 0
	s_add_i32 s64, 0, 0x18000
	s_add_i32 s65, 0, 0x1c000
	s_add_u32 s44, s44, s26
	s_addc_u32 s45, s45, 0
	s_mov_b32 m0, s95
	v_lshl_add_u64 v[238:239], s[44:45], 0, v[182:183]
	global_load_lds_dwordx4 v[238:239], off
	s_mov_b32 m0, s96
	v_lshl_add_u64 v[238:239], s[44:45], 0, v[186:187]
	global_load_lds_dwordx4 v[238:239], off
	s_setprio 1
	s_waitcnt vmcnt(8) lgkmcnt(0)
	s_barrier
	v_mfma_f32_16x16x32_bf16 v[126:129], v[130:133], v[162:165], v[126:129]
	v_mfma_f32_16x16x32_bf16 v[122:125], v[138:141], v[162:165], v[122:125]
	v_mfma_f32_16x16x32_bf16 v[110:113], v[130:133], v[170:173], v[110:113]
	v_mfma_f32_16x16x32_bf16 v[102:105], v[138:141], v[170:173], v[102:105]
	v_mfma_f32_16x16x32_bf16 v[94:97], v[130:133], v[178:181], v[94:97]
	v_mfma_f32_16x16x32_bf16 v[86:89], v[138:141], v[178:181], v[86:89]
	v_mfma_f32_16x16x32_bf16 v[78:81], v[130:133], v[198:201], v[78:81]
	v_mfma_f32_16x16x32_bf16 v[70:73], v[138:141], v[198:201], v[70:73]
	v_mfma_f32_16x16x32_bf16 v[126:129], v[134:137], v[166:169], v[126:129]
	v_mfma_f32_16x16x32_bf16 v[122:125], v[142:145], v[166:169], v[122:125]
	v_mfma_f32_16x16x32_bf16 v[110:113], v[134:137], v[174:177], v[110:113]
	v_mfma_f32_16x16x32_bf16 v[102:105], v[142:145], v[174:177], v[102:105]
	v_mfma_f32_16x16x32_bf16 v[94:97], v[134:137], v[194:197], v[94:97]
	v_mfma_f32_16x16x32_bf16 v[86:89], v[142:145], v[194:197], v[86:89]
	v_mfma_f32_16x16x32_bf16 v[78:81], v[134:137], v[202:205], v[78:81]
	v_mfma_f32_16x16x32_bf16 v[70:73], v[142:145], v[202:205], v[70:73]
	v_mfma_f32_16x16x32_bf16 v[118:121], v[146:149], v[162:165], v[118:121]
	v_mfma_f32_16x16x32_bf16 v[114:117], v[154:157], v[162:165], v[114:117]
	v_mfma_f32_16x16x32_bf16 v[106:109], v[146:149], v[170:173], v[106:109]
	v_mfma_f32_16x16x32_bf16 v[98:101], v[154:157], v[170:173], v[98:101]
	v_mfma_f32_16x16x32_bf16 v[90:93], v[146:149], v[178:181], v[90:93]
	v_mfma_f32_16x16x32_bf16 v[82:85], v[154:157], v[178:181], v[82:85]
	v_mfma_f32_16x16x32_bf16 v[74:77], v[146:149], v[198:201], v[74:77]
	v_mfma_f32_16x16x32_bf16 v[66:69], v[154:157], v[198:201], v[66:69]
	v_mfma_f32_16x16x32_bf16 v[118:121], v[150:153], v[166:169], v[118:121]
	v_mfma_f32_16x16x32_bf16 v[114:117], v[158:161], v[166:169], v[114:117]
	v_mfma_f32_16x16x32_bf16 v[106:109], v[150:153], v[174:177], v[106:109]
	v_mfma_f32_16x16x32_bf16 v[98:101], v[158:161], v[174:177], v[98:101]
	v_mfma_f32_16x16x32_bf16 v[90:93], v[150:153], v[194:197], v[90:93]
	v_mfma_f32_16x16x32_bf16 v[82:85], v[158:161], v[194:197], v[82:85]
	v_mfma_f32_16x16x32_bf16 v[74:77], v[150:153], v[202:205], v[74:77]
	v_mfma_f32_16x16x32_bf16 v[66:69], v[158:161], v[202:205], v[66:69]
	s_barrier
; #define PG8_STAGE(bufoff, gbase, voff) do { _Pragma("unroll") for (int _i = 0; _i < 2; ++_i) \
;         __builtin_amdgcn_global_load_lds((const unsigned*)((const char*)(gbase) + (voff)[_i]), (PG8_LAS unsigned*)(lds + (bufoff) + ldsw + _i * 8192), 16, 0, 0); } while (0)
; #define PG8_LDA(dst, b, h) do { _Pragma("unroll") for (int m = 0; m < 4; ++m) _Pragma("unroll") for (int k = 0; k < 2; ++k) dst[m][k] = *(const PG8_LAS bf16x8*)(lds + PG8_SA(b, h) + aoff + m * 2048 + k * 1024); } while (0)
; #define PG8_MMA(ai, bj, At, Bt) do { __builtin_amdgcn_s_setprio(1); _Pragma("unroll") for (int m = 0; m < 4; ++m) _Pragma("unroll") for (int n = 0; n < 2; ++n) _Pragma("unroll") for (int k = 0; k < 2; ++k) \
;         acc[ai][bj][m][n] = __builtin_amdgcn_mfma_f32_16x16x32_bf16(Bt[n][k], At[m][k], acc[ai][bj][m][n], 0, 0, 0); __builtin_amdgcn_s_setprio(0); } while (0)
; #define PG8_WAIT_V(n) asm volatile("s_waitcnt vmcnt(" #n ")" ::: "memory")
; #define PG8_WAIT_L(n) asm volatile("s_waitcnt lgkmcnt(" #n ")" ::: "memory")
; #define PG8_BAR __builtin_amdgcn_s_barrier()
; #define PG8_SCHED __builtin_amdgcn_sched_barrier(0)
; template <class Epi, class Sched, bool ALIGN_EPI = false, bool SP2 = false>
; __device__ __forceinline__ void gemm_phase(PG8_LAS unsigned char* lds, const Gemm g, const Sched& S, const Epi& E) {
;     ...
;             PG8_LDA(At, 1, 1); PG8_STAGE(PG8_SB(1, 0), b3, voffB); PG8_STAGE(PG8_SB(1, 1), b3 + hstep, voffB); PG8_STAGE(PG8_SA(1, 0), a3, voffA);
;             PG8_WAIT_V(8); PG8_WAIT_L(0); PG8_BAR; PG8_MMA(1, 0, At, B0); PG8_MMA(1, 1, At, B1); PG8_BAR; PG8_SCHED;
;     ...
;         if constexpr (ALIGN_EPI) { if (wr == 0) PG8_BAR; }
;         if constexpr (!Epi::AFTER_DRAIN) { E(acc, cur, wr, wc, fr, fq); S.done(cur); }
;         if (!has_next) break;
	ds_read_b128 v[162:165], v230 offset:49152
	ds_read_b128 v[166:169], v230 offset:50176
	ds_read_b128 v[170:173], v230 offset:51200
	ds_read_b128 v[174:177], v230 offset:52224
	ds_read_b128 v[178:181], v230 offset:53248
	ds_read_b128 v[194:197], v230 offset:54272
	ds_read_b128 v[198:201], v230 offset:55296
	ds_read_b128 v[202:205], v230 offset:56320
	s_setprio 0
	s_add_i32 s44, s64, s92
	s_mov_b32 m0, s44
	v_lshl_add_u64 v[206:207], v[206:207], 0, s[34:35]
	global_load_lds_dwordx4 v[206:207], off
	v_lshl_add_u64 v[206:207], v[208:209], 0, s[34:35]
	s_add_i32 m0, s44, 0x2000
	s_add_i32 s44, s65, s92
	global_load_lds_dwordx4 v[206:207], off
	s_mov_b32 m0, s44
	v_lshl_add_u64 v[206:207], v[210:211], 0, s[34:35]
	global_load_lds_dwordx4 v[206:207], off
	s_add_i32 m0, s44, 0x2000
	v_lshl_add_u64 v[206:207], v[232:233], 0, s[34:35]
	global_load_lds_dwordx4 v[206:207], off
	s_mov_b32 m0, s97
	v_lshl_add_u64 v[206:207], v[234:235], 0, s[34:35]
	global_load_lds_dwordx4 v[206:207], off
	s_mov_b32 m0, s98
	v_lshl_add_u64 v[206:207], v[236:237], 0, s[34:35]
	global_load_lds_dwordx4 v[206:207], off
	s_add_u32 s42, s42, 0x100
	s_addc_u32 s43, s43, 0
	s_add_u32 s17, s17, 0x100
	s_addc_u32 s60, s60, 0
	s_cmp_ge_u32 s61, s4
	s_mov_b32 s44, s61
	s_setprio 1
	s_waitcnt vmcnt(8) lgkmcnt(0)
	s_barrier
	v_mfma_f32_16x16x32_bf16 v[62:65], v[130:133], v[162:165], v[62:65]
	v_mfma_f32_16x16x32_bf16 v[54:57], v[138:141], v[162:165], v[54:57]
	v_mfma_f32_16x16x32_bf16 v[46:49], v[130:133], v[170:173], v[46:49]
	v_mfma_f32_16x16x32_bf16 v[38:41], v[138:141], v[170:173], v[38:41]
	v_mfma_f32_16x16x32_bf16 v[30:33], v[130:133], v[178:181], v[30:33]
	v_mfma_f32_16x16x32_bf16 v[22:25], v[138:141], v[178:181], v[22:25]
	v_mfma_f32_16x16x32_bf16 v[14:17], v[130:133], v[198:201], v[14:17]
	v_mfma_f32_16x16x32_bf16 v[6:9], v[138:141], v[198:201], v[6:9]
	v_mfma_f32_16x16x32_bf16 v[62:65], v[134:137], v[166:169], v[62:65]
	v_mfma_f32_16x16x32_bf16 v[54:57], v[142:145], v[166:169], v[54:57]
	v_mfma_f32_16x16x32_bf16 v[46:49], v[134:137], v[174:177], v[46:49]
	v_mfma_f32_16x16x32_bf16 v[38:41], v[142:145], v[174:177], v[38:41]
	v_mfma_f32_16x16x32_bf16 v[30:33], v[134:137], v[194:197], v[30:33]
	v_mfma_f32_16x16x32_bf16 v[22:25], v[142:145], v[194:197], v[22:25]
	v_mfma_f32_16x16x32_bf16 v[14:17], v[134:137], v[202:205], v[14:17]
	v_mfma_f32_16x16x32_bf16 v[6:9], v[142:145], v[202:205], v[6:9]
	v_mfma_f32_16x16x32_bf16 v[58:61], v[146:149], v[162:165], v[58:61]
	v_mfma_f32_16x16x32_bf16 v[50:53], v[154:157], v[162:165], v[50:53]
	v_mfma_f32_16x16x32_bf16 v[42:45], v[146:149], v[170:173], v[42:45]
	v_mfma_f32_16x16x32_bf16 v[34:37], v[154:157], v[170:173], v[34:37]
	v_mfma_f32_16x16x32_bf16 v[26:29], v[146:149], v[178:181], v[26:29]
	v_mfma_f32_16x16x32_bf16 v[18:21], v[154:157], v[178:181], v[18:21]
	v_mfma_f32_16x16x32_bf16 v[10:13], v[146:149], v[198:201], v[10:13]
	v_mfma_f32_16x16x32_bf16 v[2:5], v[154:157], v[198:201], v[2:5]
	v_mfma_f32_16x16x32_bf16 v[58:61], v[150:153], v[166:169], v[58:61]
	v_mfma_f32_16x16x32_bf16 v[50:53], v[158:161], v[166:169], v[50:53]
	v_mfma_f32_16x16x32_bf16 v[42:45], v[150:153], v[174:177], v[42:45]
	v_mfma_f32_16x16x32_bf16 v[34:37], v[158:161], v[174:177], v[34:37]
	v_mfma_f32_16x16x32_bf16 v[26:29], v[150:153], v[194:197], v[26:29]
	v_mfma_f32_16x16x32_bf16 v[18:21], v[158:161], v[194:197], v[18:21]
	v_mfma_f32_16x16x32_bf16 v[10:13], v[150:153], v[202:205], v[10:13]
	v_mfma_f32_16x16x32_bf16 v[2:5], v[158:161], v[202:205], v[2:5]
	s_barrier
	s_cbranch_scc0 .LBB0_441
	s_setprio 0
	s_and_b64 vcc, exec, s[36:37]
	s_cbranch_vccz .LBB0_445
	s_barrier
	s_cmp_lt_i32 s0, 2
	s_mov_b64 s[42:43], -1
	s_cbranch_scc0 .LBB0_446
